# FFN1 epilogue: rstd of the next unit prefetched during the current epilogue (no exposed L2 latency per unit)
# speedup vs baseline: 1.0054x; 1.0041x over previous
; __device__ __forceinline__ int lane_now() { int l; asm volatile("v_mbcnt_lo_u32_b32 %0, -1, 0\n\tv_mbcnt_hi_u32_b32 %0, -1, %0" : "=v"(l)); return l; }
; #define PG8_LAS __attribute__((address_space(3)))
; #define PG8_WAIT_V(n) asm volatile("s_waitcnt vmcnt(" #n ")" ::: "memory")
; #define PG8_BAR __builtin_amdgcn_s_barrier()
;     __host__ __device__ bool next(int i, Unit& u) const {
;         const long L = (long)i * G + c; if (L >= nwg) return false;
;         int wgid = (int)L; { const int q = nwg / NXCD, r = nwg % NXCD, xcd = wgid % NXCD, off = wgid / NXCD; wgid = (xcd < r ? xcd * (q + 1) : r * (q + 1) + (xcd - r) * q) + off; }
;         const int nig = WGM * nN, gid = wgid / nig, fm = gid * WGM, gsz = (nM - fm) < WGM ? (nM - fm) : WGM;
;         u.pm = fm + ((wgid % nig) % gsz); u.pn = (wgid % nig) / gsz; return true;
;     }
; __device__ __forceinline__ unsigned cvt_pk_bf16(float lo, float hi) { unsigned r; asm volatile("v_cvt_pk_bf16_f32 %0, %1, %2" : "=v"(r) : "v"(lo), "v"(hi)); return r; }
; template <class Epi, class Sched, bool ALIGN_EPI = false, bool SP2 = false>
; __device__ __forceinline__ void gemm_phase(PG8_LAS unsigned char* lds, const Gemm g, const Sched& S, const Epi& E, const int wid) {
;     const int lane = lane_now(), tid = wid * 64 + lane, wr = wid >> 2, wc = wid & 3, fr = lane & 15, fq = lane >> 4;
;     const int K = g.K, nt = K / BK;
;     unsigned voffA[2], voffB[2];
; #pragma unroll
;     for (int i = 0; i < 2; ++i) { int R, C; stage_rc(tid * 16 + i * 8192, R, C); const int Rb = Epi::PERM ? ((R & ~31) + perm32(R & 31)) : R;
;         voffA[i] = (unsigned)(R * K + C) * 2u; voffB[i] = (unsigned)(Rb * K + C) * 2u; }
;     const size_t kstep = (size_t)(BK * 2);
;     const size_t hstep = (size_t)HALF * K * 2;
;     const size_t tstep = 2 * hstep;
;     const unsigned ldsw = (unsigned)wid * 1024u;
;     const int aoff = lds_byte(wr * 64 + fr, fq * 8), boff = lds_byte(wc * 32 + fr, fq * 8);
;     ...
;         PG8_STAGE(PG8_SB(0, 0), cB, voffB); PG8_STAGE(PG8_SB(0, 1), cB + hstep, voffB); PG8_STAGE(PG8_SA(0, 0), cA, voffA); PG8_STAGE(PG8_SA(0, 1), cA + hstep, voffA);
;         if (wr == 1) PG8_BAR;
;         PG8_WAIT_V(2); PG8_BAR;
;         PG8_STAGE(PG8_SB(1, 0), cB + kstep, voffB); PG8_STAGE(PG8_SA(1, 0), cA + kstep, voffA); PG8_STAGE(PG8_SB(1, 1), cB + hstep + kstep, voffB);
;         PG8_WAIT_V(6); PG8_BAR;
.LBB0_1479:
	s_mov_b32 s101, 0
	s_load_dword s0, s[88:89], 0xd8
	s_waitcnt lgkmcnt(0)
	s_cmp_gt_i32 s0, 14
	s_cbranch_scc1 .LBB0_1558
	s_load_dword s0, s[88:89], 0xdc
	s_waitcnt lgkmcnt(0)
	s_cmp_lt_i32 s0, 15
	s_cbranch_scc1 .LBB0_1558
	v_readlane_b32 s0, v231, 1
	v_readlane_b32 s1, v231, 2
	s_load_dword s48, s[0:1], 0xe0
	s_movk_i32 s0, 0x2c00
	s_movk_i32 s4, 0x800
	s_load_dwordx2 s[10:11], s[88:89], 0xd0
	s_ashr_i32 s1, s0, 31
	s_lshr_b32 s1, s1, 24
	s_add_i32 s0, s0, s1
	s_ashr_i32 s1, s0, 8
	s_lshl_b32 s2, s1, 6
	v_readlane_b32 s0, v231, 0
	s_cmp_ge_i32 s0, s2
	v_mbcnt_lo_u32_b32 v12, -1, 0
	v_mbcnt_hi_u32_b32 v12, -1, v12
	s_cbranch_scc1 .LBB0_1502
	s_waitcnt lgkmcnt(0)
	s_add_u32 s30, s10, 0x1a400000
	s_addc_u32 s31, s11, 0
	s_add_u32 s34, s10, 0xe200000
	s_addc_u32 s35, s11, 0
	s_lshl_b32 s36, s92, 10
	v_lshl_add_u32 v0, v12, 4, s36
	v_add_u32_e32 v1, 0x2000, v0
	v_ashrrev_i32_e32 v2, 31, v1
	v_lshrrev_b32_e32 v2, 22, v2
	v_add_u32_e32 v2, v1, v2
	v_ashrrev_i32_e32 v2, 10, v2
	v_mul_i32_i24_e32 v3, 0x400, v2
	v_sub_u32_e32 v1, v1, v3
	v_lshrrev_b32_e32 v3, 4, v1
	v_bitop3_b32 v1, v3, v1, 32 bitop3:0x6c
	v_ashrrev_i32_e32 v3, 31, v1
	v_lshrrev_b32_e32 v3, 26, v3
	v_add_u32_e32 v3, v1, v3
	v_lshlrev_b32_e32 v5, 3, v2
	v_lshlrev_b32_e32 v2, 5, v2
	v_and_b32_e32 v13, 32, v2
	v_and_b32_e32 v2, 0xffc0, v3
	v_sub_u32_e32 v1, v1, v2
	v_ashrrev_i32_e32 v4, 6, v3
	v_and_b32_e32 v5, -16, v5
	v_lshrrev_b16_e32 v2, 7, v1
	v_add_u32_e32 v5, v4, v5
	v_and_b32_e32 v2, 1, v2
	v_and_b32_e32 v4, 3, v4
	s_mov_b32 s3, 0x7fffffe0
	v_lshrrev_b32_e32 v6, 2, v5
	v_lshlrev_b32_e32 v7, 1, v5
	v_add_u16_e32 v1, v1, v2
	v_mov_b32_e32 v2, 1
	v_and_or_b32 v4, v5, s3, v4
	v_and_b32_e32 v6, 4, v6
	v_and_b32_e32 v7, 24, v7
	v_ashrrev_i16_sdwa v1, v2, sext(v1) dst_sel:DWORD dst_unused:UNUSED_PAD src0_sel:DWORD src1_sel:BYTE_0
	v_or3_b32 v4, v4, v6, v7
	v_bfe_i32 v14, v1, 0, 16
	v_mul_lo_u32 v4, v4, s4
	v_add_u32_e32 v1, v13, v14
	v_mul_lo_u32 v15, v5, s4
	s_waitcnt vmcnt(0)
	v_add_lshl_u32 v128, v4, v1, 1
	v_add_lshl_u32 v130, v1, v15, 1
	v_ashrrev_i32_e32 v1, 31, v0
	v_lshrrev_b32_e32 v1, 22, v1
	v_add_u32_e32 v1, v0, v1
	v_ashrrev_i32_e32 v1, 10, v1
	v_mul_i32_i24_e32 v3, 0x400, v1
	v_sub_u32_e32 v0, v0, v3
	v_lshrrev_b32_e32 v3, 4, v0
	v_bitop3_b32 v0, v3, v0, 32 bitop3:0x6c
	v_ashrrev_i32_e32 v3, 31, v0
	v_lshrrev_b32_e32 v3, 26, v3
	v_add_u32_e32 v3, v0, v3
	v_lshlrev_b32_e32 v5, 3, v1
	v_ashrrev_i32_e32 v4, 6, v3
	v_and_b32_e32 v5, -16, v5
	v_readlane_b32 s7, v231, 0
	v_add_u32_e32 v5, v4, v5
	v_and_b32_e32 v4, 3, v4
	s_ashr_i32 s38, s7, 31
	v_and_or_b32 v4, v5, s3, v4
	s_lshr_b32 s3, s38, 29
	s_add_i32 s3, s7, s3
	s_ashr_i32 s5, s4, 31
	s_lshl_b32 s37, s1, 3
	s_ashr_i32 s6, s3, 3
	s_and_b32 s3, s3, -8
	s_ashr_i32 s0, s92, 2
	s_lshl_b64 s[12:13], s[4:5], 8
	s_lshl_b64 s[14:15], s[4:5], 9
	s_sub_i32 s3, s7, s3
	s_or_b32 s39, s37, 1
	s_cmp_lt_i32 s3, 0
	v_lshlrev_b32_e32 v1, 5, v1
	s_cselect_b32 s7, s39, s37
	s_lshl_b32 s40, s1, 2
	v_and_b32_e32 v16, 32, v1
	v_and_b32_e32 v1, 0xc0, v3
	s_abs_i32 s41, s40
	v_sub_u32_e32 v0, v0, v1
	v_cvt_f32_u32_e32 v1, s41
	s_mul_i32 s3, s7, s3
	s_sub_i32 s7, 0, s41
	s_add_i32 s3, s3, s6
	v_rcp_iflag_f32_e32 v1, v1
	s_ashr_i32 s6, s3, 31
	s_bfe_i32 s42, s1, 0x1001d
	s_xor_b32 s1, s6, s42
	v_mul_f32_e32 v1, 0x4f7ffffe, v1
	v_cvt_u32_f32_e32 v1, v1
	s_abs_i32 s6, s3
	v_lshrrev_b32_e32 v6, 2, v5
	v_lshlrev_b32_e32 v7, 1, v5
	v_readfirstlane_b32 s43, v1
	s_mul_i32 s7, s7, s43
	s_mul_hi_u32 s7, s43, s7
	s_add_i32 s43, s43, s7
	s_mul_hi_u32 s7, s6, s43
	s_mul_i32 s8, s7, s41
	s_sub_i32 s6, s6, s8
	s_add_i32 s8, s7, 1
	s_sub_i32 s9, s6, s41
	s_cmp_ge_u32 s6, s41
	s_cselect_b32 s7, s8, s7
	s_cselect_b32 s6, s9, s6
	s_add_i32 s8, s7, 1
	s_cmp_ge_u32 s6, s41
	s_cselect_b32 s6, s8, s7
	s_xor_b32 s6, s6, s1
	s_sub_i32 s1, s6, s1
	s_lshl_b32 s6, s1, 2
	s_sub_i32 s7, 64, s6
	s_min_i32 s7, s7, 4
	s_abs_i32 s8, s7
	v_cvt_f32_u32_e32 v1, s8
	v_and_b32_e32 v6, 4, v6
	v_and_b32_e32 v7, 24, v7
	v_ashrrev_i16_sdwa v0, v2, sext(v0) dst_sel:DWORD dst_unused:UNUSED_PAD src0_sel:DWORD src1_sel:BYTE_0
	v_or3_b32 v4, v4, v6, v7
	v_bfe_i32 v17, v0, 0, 16
	v_mul_lo_u32 v4, v4, s4
	v_add_u32_e32 v0, v16, v17
	v_mul_lo_u32 v18, v5, s4
	v_add_lshl_u32 v132, v4, v0, 1
	v_add_lshl_u32 v134, v0, v18, 1
	v_rcp_iflag_f32_e32 v0, v1
	s_sub_i32 s16, 0, s8
	s_mul_i32 s1, s1, s40
	s_sub_i32 s1, s3, s1
	v_mul_f32_e32 v0, 0x4f7ffffe, v0
	v_cvt_u32_f32_e32 v0, v0
	s_abs_i32 s9, s1
	s_xor_b32 s3, s1, s7
	s_ashr_i32 s3, s3, 31
	v_readfirstlane_b32 s17, v0
	s_mul_i32 s16, s16, s17
	s_mul_hi_u32 s16, s17, s16
	s_add_i32 s17, s17, s16
	s_mul_hi_u32 s16, s9, s17
	s_mul_i32 s17, s16, s8
	s_sub_i32 s9, s9, s17
	s_add_i32 s17, s16, 1
	s_sub_i32 s18, s9, s8
	s_cmp_ge_u32 s9, s8
	s_cselect_b32 s16, s17, s16
	s_cselect_b32 s9, s18, s9
	s_add_i32 s17, s16, 1
	s_cmp_ge_u32 s9, s8
	s_cselect_b32 s8, s17, s16
	s_xor_b32 s8, s8, s3
	s_sub_i32 s62, s8, s3
	s_mul_i32 s3, s62, s7
	s_sub_i32 s1, s1, s3
	s_add_i32 s63, s1, s6
	s_lshr_b64 s[6:7], s[4:5], 23
	s_ashr_i32 s1, s63, 31
	s_ashr_i32 s7, s62, 31
	s_mul_i32 s1, s14, s1
	s_mul_hi_u32 s3, s14, s63
	s_mul_i32 s7, s14, s7
	s_mul_hi_u32 s8, s14, s62
	s_add_i32 s1, s3, s1
	s_mul_i32 s3, s6, s63
	s_add_i32 s7, s8, s7
	s_mul_i32 s6, s6, s62
	s_add_i32 s1, s1, s3
	s_add_i32 s7, s7, s6
	s_mul_i32 s6, s14, s62
	s_add_u32 s6, s34, s6
	s_addc_u32 s7, s35, s7
	s_add_i32 s44, s36, 0
	s_add_i32 m0, s44, 0x10000
	s_mul_i32 s3, s14, s63
	global_load_lds_dwordx4 v132, s[6:7]
	s_add_i32 m0, s44, 0x12000
	s_add_u32 s16, s6, s12
	global_load_lds_dwordx4 v128, s[6:7]
	s_addc_u32 s17, s7, s13
	s_add_i32 m0, s44, 0x14000
	v_mov_b32_e32 v133, 0
	global_load_lds_dwordx4 v132, s[16:17]
	s_add_i32 m0, s44, 0x16000
	s_add_u32 s8, s30, s3
	s_addc_u32 s9, s31, s1
	s_add_i32 s45, s44, 0x2000
	global_load_lds_dwordx4 v128, s[16:17]
	s_mov_b32 m0, s44
	s_add_u32 s18, s8, s12
	global_load_lds_dwordx4 v134, s[8:9]
	s_mov_b32 m0, s45
	s_addc_u32 s19, s9, s13
	s_add_i32 s46, s44, 0x4000
	global_load_lds_dwordx4 v130, s[8:9]
	s_mov_b32 m0, s46
	s_add_i32 s47, s44, 0x6000
	global_load_lds_dwordx4 v134, s[18:19]
	s_mov_b32 m0, s47
	v_mov_b32_e32 v129, v133
	global_load_lds_dwordx4 v130, s[18:19]
	v_mov_b32_e32 v135, v133
	v_mov_b32_e32 v131, v133
	s_cmp_eq_u32 s0, 1
	s_mov_b32 s49, 0
	v_lshl_add_u64 v[8:9], s[6:7], 0, v[132:133]
	v_lshl_add_u64 v[4:5], s[6:7], 0, v[128:129]
	v_lshl_add_u64 v[2:3], s[16:17], 0, v[132:133]
	v_lshl_add_u64 v[0:1], s[16:17], 0, v[128:129]
	v_lshl_add_u64 v[6:7], s[8:9], 0, v[134:135]
	s_cselect_b64 s[16:17], -1, 0
	s_cmp_lg_u32 s0, 1
	v_lshl_add_u64 v[10:11], s[8:9], 0, v[130:131]
	s_cbranch_scc1 .LBB0_1484
	s_barrier

.LBB0_1498:
	v_mov_b32_e32 v153, v146
	s_lshl_b32 s0, s63, 8
	s_add_i32 s0, s0, s53
	v_add_u32_e32 v142, s0, v147
	v_ashrrev_i32_e32 v143, 31, v142
	s_cmp_lg_u32 s101, 0
	s_cbranch_scc1 .Lf1_have
	v_lshl_add_u64 v[144:145], v[142:143], 2, s[18:19]
	global_load_dword v240, v[144:145], off
	global_load_dword v241, v[144:145], off offset:64
	global_load_dword v242, v[144:145], off offset:128
	global_load_dword v243, v[144:145], off offset:192
	global_load_dword v244, v[144:145], off offset:512
	global_load_dword v245, v[144:145], off offset:576
	global_load_dword v246, v[144:145], off offset:640
	global_load_dword v247, v[144:145], off offset:704
	s_mov_b32 s101, 1
.Lf1_have:
	s_lshl_b32 s0, s62, 7
	s_or_b32 s0, s0, s54
	v_lshl_add_u32 v156, v153, 3, s0
	v_ashrrev_i32_e32 v157, 31, v156
	v_mov_b64_e32 v[162:163], s[10:11]
	v_mad_i64_i32 v[160:161], s[0:1], v142, s59, v[162:163]
	v_lshlrev_b64 v[162:163], 1, v[156:157]
	v_lshl_add_u64 v[160:161], v[160:161], 0, v[162:163]
	v_mov_b32_e32 v164, 1.0
	v_mov_b32_e32 v165, 1.0
	s_lshl_b32 s0, s61, 8
	s_add_i32 s0, s0, s53
	v_add_u32_e32 v144, s0, v147
	v_ashrrev_i32_e32 v145, 31, v144
	v_lshl_add_u64 v[144:145], v[144:145], 2, s[18:19]
	s_waitcnt vmcnt(0)
	v_mov_b32_e32 v152, v240
	v_mov_b32_e32 v233, v241
	v_mov_b32_e32 v234, v242
	v_mov_b32_e32 v235, v243
	v_mov_b32_e32 v236, v244
	v_mov_b32_e32 v237, v245
	v_mov_b32_e32 v238, v246
	v_mov_b32_e32 v239, v247
	global_load_dword v240, v[144:145], off
	global_load_dword v241, v[144:145], off offset:64
	global_load_dword v242, v[144:145], off offset:128
	global_load_dword v243, v[144:145], off offset:192
	global_load_dword v244, v[144:145], off offset:512
	global_load_dword v245, v[144:145], off offset:576
	global_load_dword v246, v[144:145], off offset:640
	global_load_dword v247, v[144:145], off offset:704
	v_mul_f32_e32 v166, 0xbfb8aa3b, v152
	v_mul_f32_e32 v168, v152, v152
	v_pk_mul_f32 v[170:171], v[120:121], v[166:167] op_sel_hi:[1,0]
	v_pk_mul_f32 v[172:173], v[122:123], v[166:167] op_sel_hi:[1,0]
	v_pk_mul_f32 v[174:175], v[112:113], v[166:167] op_sel_hi:[1,0]
	v_pk_mul_f32 v[176:177], v[114:115], v[166:167] op_sel_hi:[1,0]
	v_pk_mul_f32 v[178:179], v[120:121], v[124:125]
	v_pk_mul_f32 v[180:181], v[122:123], v[126:127]
	v_pk_mul_f32 v[182:183], v[112:113], v[116:117]
	v_pk_mul_f32 v[184:185], v[114:115], v[118:119]
	v_exp_f32_e32 v170, v170
	v_exp_f32_e32 v171, v171
	v_exp_f32_e32 v172, v172
	v_exp_f32_e32 v173, v173
	v_exp_f32_e32 v174, v174
	v_exp_f32_e32 v175, v175
	v_exp_f32_e32 v176, v176
	v_exp_f32_e32 v177, v177
	s_nop 0
	v_pk_add_f32 v[170:171], v[170:171], v[164:165]
	v_pk_add_f32 v[172:173], v[172:173], v[164:165]
	v_pk_add_f32 v[174:175], v[174:175], v[164:165]
	v_pk_add_f32 v[176:177], v[176:177], v[164:165]
	v_rcp_f32_e32 v170, v170
	v_rcp_f32_e32 v171, v171
	v_rcp_f32_e32 v172, v172
	v_rcp_f32_e32 v173, v173
	v_rcp_f32_e32 v174, v174
	v_rcp_f32_e32 v175, v175
	v_rcp_f32_e32 v176, v176
	v_rcp_f32_e32 v177, v177
	s_nop 0
	v_pk_mul_f32 v[170:171], v[170:171], v[168:169] op_sel_hi:[1,0]
	v_pk_mul_f32 v[172:173], v[172:173], v[168:169] op_sel_hi:[1,0]
	v_pk_mul_f32 v[174:175], v[174:175], v[168:169] op_sel_hi:[1,0]
	v_pk_mul_f32 v[176:177], v[176:177], v[168:169] op_sel_hi:[1,0]
	v_pk_mul_f32 v[178:179], v[178:179], v[170:171]
	v_pk_mul_f32 v[180:181], v[180:181], v[172:173]
	v_pk_mul_f32 v[182:183], v[182:183], v[174:175]
	v_pk_mul_f32 v[184:185], v[184:185], v[176:177]
	v_cvt_pk_bf16_f32 v186, v178, v179
	v_cvt_pk_bf16_f32 v187, v180, v181
	v_cvt_pk_bf16_f32 v188, v182, v183
	v_cvt_pk_bf16_f32 v189, v184, v185
	global_store_dwordx4 v[160:161], v[186:189], off
	s_nop 1
	s_mov_b64 s[98:99], 0x2c000
	v_lshl_add_u64 v[160:161], v[160:161], 0, s[98:99]
	v_mul_f32_e32 v166, 0xbfb8aa3b, v233
	v_mul_f32_e32 v168, v233, v233
	v_pk_mul_f32 v[170:171], v[104:105], v[166:167] op_sel_hi:[1,0]
	v_pk_mul_f32 v[172:173], v[106:107], v[166:167] op_sel_hi:[1,0]
	v_pk_mul_f32 v[174:175], v[96:97], v[166:167] op_sel_hi:[1,0]
	v_pk_mul_f32 v[176:177], v[98:99], v[166:167] op_sel_hi:[1,0]
	v_pk_mul_f32 v[178:179], v[104:105], v[108:109]
	v_pk_mul_f32 v[180:181], v[106:107], v[110:111]
	v_pk_mul_f32 v[182:183], v[96:97], v[100:101]
	v_pk_mul_f32 v[184:185], v[98:99], v[102:103]
	v_exp_f32_e32 v170, v170
	v_exp_f32_e32 v171, v171
	v_exp_f32_e32 v172, v172
	v_exp_f32_e32 v173, v173
	v_exp_f32_e32 v174, v174
	v_exp_f32_e32 v175, v175
	v_exp_f32_e32 v176, v176
	v_exp_f32_e32 v177, v177
	s_nop 0
	v_pk_add_f32 v[170:171], v[170:171], v[164:165]
	v_pk_add_f32 v[172:173], v[172:173], v[164:165]
	v_pk_add_f32 v[174:175], v[174:175], v[164:165]
	v_pk_add_f32 v[176:177], v[176:177], v[164:165]
	v_rcp_f32_e32 v170, v170
	v_rcp_f32_e32 v171, v171
	v_rcp_f32_e32 v172, v172
	v_rcp_f32_e32 v173, v173
	v_rcp_f32_e32 v174, v174
	v_rcp_f32_e32 v175, v175
	v_rcp_f32_e32 v176, v176
	v_rcp_f32_e32 v177, v177
	s_nop 0
	v_pk_mul_f32 v[170:171], v[170:171], v[168:169] op_sel_hi:[1,0]
	v_pk_mul_f32 v[172:173], v[172:173], v[168:169] op_sel_hi:[1,0]
	v_pk_mul_f32 v[174:175], v[174:175], v[168:169] op_sel_hi:[1,0]
	v_pk_mul_f32 v[176:177], v[176:177], v[168:169] op_sel_hi:[1,0]
	v_pk_mul_f32 v[178:179], v[178:179], v[170:171]
	v_pk_mul_f32 v[180:181], v[180:181], v[172:173]
	v_pk_mul_f32 v[182:183], v[182:183], v[174:175]
	v_pk_mul_f32 v[184:185], v[184:185], v[176:177]
	v_cvt_pk_bf16_f32 v186, v178, v179
	v_cvt_pk_bf16_f32 v187, v180, v181
	v_cvt_pk_bf16_f32 v188, v182, v183
	v_cvt_pk_bf16_f32 v189, v184, v185
	global_store_dwordx4 v[160:161], v[186:189], off
	s_nop 1
	s_mov_b64 s[98:99], 0x2c000
	v_lshl_add_u64 v[160:161], v[160:161], 0, s[98:99]
	v_mul_f32_e32 v166, 0xbfb8aa3b, v234
	v_mul_f32_e32 v168, v234, v234
	v_pk_mul_f32 v[170:171], v[88:89], v[166:167] op_sel_hi:[1,0]
	v_pk_mul_f32 v[172:173], v[90:91], v[166:167] op_sel_hi:[1,0]
	v_pk_mul_f32 v[174:175], v[80:81], v[166:167] op_sel_hi:[1,0]
	v_pk_mul_f32 v[176:177], v[82:83], v[166:167] op_sel_hi:[1,0]
	v_pk_mul_f32 v[178:179], v[88:89], v[92:93]
	v_pk_mul_f32 v[180:181], v[90:91], v[94:95]
	v_pk_mul_f32 v[182:183], v[80:81], v[84:85]
	v_pk_mul_f32 v[184:185], v[82:83], v[86:87]
	v_exp_f32_e32 v170, v170
	v_exp_f32_e32 v171, v171
	v_exp_f32_e32 v172, v172
	v_exp_f32_e32 v173, v173
	v_exp_f32_e32 v174, v174
	v_exp_f32_e32 v175, v175
	v_exp_f32_e32 v176, v176
	v_exp_f32_e32 v177, v177
	s_nop 0
	v_pk_add_f32 v[170:171], v[170:171], v[164:165]
	v_pk_add_f32 v[172:173], v[172:173], v[164:165]
	v_pk_add_f32 v[174:175], v[174:175], v[164:165]
	v_pk_add_f32 v[176:177], v[176:177], v[164:165]
	v_rcp_f32_e32 v170, v170
	v_rcp_f32_e32 v171, v171
	v_rcp_f32_e32 v172, v172
	v_rcp_f32_e32 v173, v173
	v_rcp_f32_e32 v174, v174
	v_rcp_f32_e32 v175, v175
	v_rcp_f32_e32 v176, v176
	v_rcp_f32_e32 v177, v177
	s_nop 0
	v_pk_mul_f32 v[170:171], v[170:171], v[168:169] op_sel_hi:[1,0]
	v_pk_mul_f32 v[172:173], v[172:173], v[168:169] op_sel_hi:[1,0]
	v_pk_mul_f32 v[174:175], v[174:175], v[168:169] op_sel_hi:[1,0]
	v_pk_mul_f32 v[176:177], v[176:177], v[168:169] op_sel_hi:[1,0]
	v_pk_mul_f32 v[178:179], v[178:179], v[170:171]
	v_pk_mul_f32 v[180:181], v[180:181], v[172:173]
	v_pk_mul_f32 v[182:183], v[182:183], v[174:175]
	v_pk_mul_f32 v[184:185], v[184:185], v[176:177]
	v_cvt_pk_bf16_f32 v186, v178, v179
	v_cvt_pk_bf16_f32 v187, v180, v181
	v_cvt_pk_bf16_f32 v188, v182, v183
	v_cvt_pk_bf16_f32 v189, v184, v185
	global_store_dwordx4 v[160:161], v[186:189], off
	s_nop 1
	s_mov_b64 s[98:99], 0x2c000
	v_lshl_add_u64 v[160:161], v[160:161], 0, s[98:99]
	v_mul_f32_e32 v166, 0xbfb8aa3b, v235
	v_mul_f32_e32 v168, v235, v235
	v_pk_mul_f32 v[170:171], v[72:73], v[166:167] op_sel_hi:[1,0]
	v_pk_mul_f32 v[172:173], v[74:75], v[166:167] op_sel_hi:[1,0]
	v_pk_mul_f32 v[174:175], v[64:65], v[166:167] op_sel_hi:[1,0]
	v_pk_mul_f32 v[176:177], v[66:67], v[166:167] op_sel_hi:[1,0]
	v_pk_mul_f32 v[178:179], v[72:73], v[76:77]
	v_pk_mul_f32 v[180:181], v[74:75], v[78:79]
	v_pk_mul_f32 v[182:183], v[64:65], v[68:69]
	v_pk_mul_f32 v[184:185], v[66:67], v[70:71]
	v_exp_f32_e32 v170, v170
	v_exp_f32_e32 v171, v171
	v_exp_f32_e32 v172, v172
	v_exp_f32_e32 v173, v173
	v_exp_f32_e32 v174, v174
	v_exp_f32_e32 v175, v175
	v_exp_f32_e32 v176, v176
	v_exp_f32_e32 v177, v177
	s_nop 0
	v_pk_add_f32 v[170:171], v[170:171], v[164:165]
	v_pk_add_f32 v[172:173], v[172:173], v[164:165]
	v_pk_add_f32 v[174:175], v[174:175], v[164:165]
	v_pk_add_f32 v[176:177], v[176:177], v[164:165]
	v_rcp_f32_e32 v170, v170
	v_rcp_f32_e32 v171, v171
	v_rcp_f32_e32 v172, v172
	v_rcp_f32_e32 v173, v173
	v_rcp_f32_e32 v174, v174
	v_rcp_f32_e32 v175, v175
	v_rcp_f32_e32 v176, v176
	v_rcp_f32_e32 v177, v177
	s_nop 0
	v_pk_mul_f32 v[170:171], v[170:171], v[168:169] op_sel_hi:[1,0]
	v_pk_mul_f32 v[172:173], v[172:173], v[168:169] op_sel_hi:[1,0]
	v_pk_mul_f32 v[174:175], v[174:175], v[168:169] op_sel_hi:[1,0]
	v_pk_mul_f32 v[176:177], v[176:177], v[168:169] op_sel_hi:[1,0]
	v_pk_mul_f32 v[178:179], v[178:179], v[170:171]
	v_pk_mul_f32 v[180:181], v[180:181], v[172:173]
	v_pk_mul_f32 v[182:183], v[182:183], v[174:175]
	v_pk_mul_f32 v[184:185], v[184:185], v[176:177]
	v_cvt_pk_bf16_f32 v186, v178, v179
	v_cvt_pk_bf16_f32 v187, v180, v181
	v_cvt_pk_bf16_f32 v188, v182, v183
	v_cvt_pk_bf16_f32 v189, v184, v185
	global_store_dwordx4 v[160:161], v[186:189], off
	s_nop 1
	s_mov_b64 s[98:99], 0xdc000
	v_lshl_add_u64 v[160:161], v[160:161], 0, s[98:99]
	v_mul_f32_e32 v166, 0xbfb8aa3b, v236
	v_mul_f32_e32 v168, v236, v236
	v_pk_mul_f32 v[170:171], v[56:57], v[166:167] op_sel_hi:[1,0]
	v_pk_mul_f32 v[172:173], v[58:59], v[166:167] op_sel_hi:[1,0]
	v_pk_mul_f32 v[174:175], v[48:49], v[166:167] op_sel_hi:[1,0]
	v_pk_mul_f32 v[176:177], v[50:51], v[166:167] op_sel_hi:[1,0]
	v_pk_mul_f32 v[178:179], v[56:57], v[60:61]
	v_pk_mul_f32 v[180:181], v[58:59], v[62:63]
	v_pk_mul_f32 v[182:183], v[48:49], v[52:53]
	v_pk_mul_f32 v[184:185], v[50:51], v[54:55]
	v_exp_f32_e32 v170, v170
	v_exp_f32_e32 v171, v171
	v_exp_f32_e32 v172, v172
	v_exp_f32_e32 v173, v173
	v_exp_f32_e32 v174, v174
	v_exp_f32_e32 v175, v175
	v_exp_f32_e32 v176, v176
	v_exp_f32_e32 v177, v177
	s_nop 0
	v_pk_add_f32 v[170:171], v[170:171], v[164:165]
	v_pk_add_f32 v[172:173], v[172:173], v[164:165]
	v_pk_add_f32 v[174:175], v[174:175], v[164:165]
	v_pk_add_f32 v[176:177], v[176:177], v[164:165]
	v_rcp_f32_e32 v170, v170
	v_rcp_f32_e32 v171, v171
	v_rcp_f32_e32 v172, v172
	v_rcp_f32_e32 v173, v173
	v_rcp_f32_e32 v174, v174
	v_rcp_f32_e32 v175, v175
	v_rcp_f32_e32 v176, v176
	v_rcp_f32_e32 v177, v177
	s_nop 0
	v_pk_mul_f32 v[170:171], v[170:171], v[168:169] op_sel_hi:[1,0]
	v_pk_mul_f32 v[172:173], v[172:173], v[168:169] op_sel_hi:[1,0]
	v_pk_mul_f32 v[174:175], v[174:175], v[168:169] op_sel_hi:[1,0]
	v_pk_mul_f32 v[176:177], v[176:177], v[168:169] op_sel_hi:[1,0]
	v_pk_mul_f32 v[178:179], v[178:179], v[170:171]
	v_pk_mul_f32 v[180:181], v[180:181], v[172:173]
	v_pk_mul_f32 v[182:183], v[182:183], v[174:175]
	v_pk_mul_f32 v[184:185], v[184:185], v[176:177]
	v_cvt_pk_bf16_f32 v186, v178, v179
	v_cvt_pk_bf16_f32 v187, v180, v181
	v_cvt_pk_bf16_f32 v188, v182, v183
	v_cvt_pk_bf16_f32 v189, v184, v185
	global_store_dwordx4 v[160:161], v[186:189], off
	s_nop 1
	s_mov_b64 s[98:99], 0x2c000
	v_lshl_add_u64 v[160:161], v[160:161], 0, s[98:99]
	v_mul_f32_e32 v166, 0xbfb8aa3b, v237
	v_mul_f32_e32 v168, v237, v237
	v_pk_mul_f32 v[170:171], v[40:41], v[166:167] op_sel_hi:[1,0]
	v_pk_mul_f32 v[172:173], v[42:43], v[166:167] op_sel_hi:[1,0]
	v_pk_mul_f32 v[174:175], v[32:33], v[166:167] op_sel_hi:[1,0]
	v_pk_mul_f32 v[176:177], v[34:35], v[166:167] op_sel_hi:[1,0]
	v_pk_mul_f32 v[178:179], v[40:41], v[44:45]
	v_pk_mul_f32 v[180:181], v[42:43], v[46:47]
	v_pk_mul_f32 v[182:183], v[32:33], v[36:37]
	v_pk_mul_f32 v[184:185], v[34:35], v[38:39]
	v_exp_f32_e32 v170, v170
	v_exp_f32_e32 v171, v171
	v_exp_f32_e32 v172, v172
	v_exp_f32_e32 v173, v173
	v_exp_f32_e32 v174, v174
	v_exp_f32_e32 v175, v175
	v_exp_f32_e32 v176, v176
	v_exp_f32_e32 v177, v177
	s_nop 0
	v_pk_add_f32 v[170:171], v[170:171], v[164:165]
	v_pk_add_f32 v[172:173], v[172:173], v[164:165]
	v_pk_add_f32 v[174:175], v[174:175], v[164:165]
	v_pk_add_f32 v[176:177], v[176:177], v[164:165]
	v_rcp_f32_e32 v170, v170
	v_rcp_f32_e32 v171, v171
	v_rcp_f32_e32 v172, v172
	v_rcp_f32_e32 v173, v173
	v_rcp_f32_e32 v174, v174
	v_rcp_f32_e32 v175, v175
	v_rcp_f32_e32 v176, v176
	v_rcp_f32_e32 v177, v177
	s_nop 0
	v_pk_mul_f32 v[170:171], v[170:171], v[168:169] op_sel_hi:[1,0]
	v_pk_mul_f32 v[172:173], v[172:173], v[168:169] op_sel_hi:[1,0]
	v_pk_mul_f32 v[174:175], v[174:175], v[168:169] op_sel_hi:[1,0]
	v_pk_mul_f32 v[176:177], v[176:177], v[168:169] op_sel_hi:[1,0]
	v_pk_mul_f32 v[178:179], v[178:179], v[170:171]
	v_pk_mul_f32 v[180:181], v[180:181], v[172:173]
	v_pk_mul_f32 v[182:183], v[182:183], v[174:175]
	v_pk_mul_f32 v[184:185], v[184:185], v[176:177]
	v_cvt_pk_bf16_f32 v186, v178, v179
	v_cvt_pk_bf16_f32 v187, v180, v181
	v_cvt_pk_bf16_f32 v188, v182, v183
	v_cvt_pk_bf16_f32 v189, v184, v185
	global_store_dwordx4 v[160:161], v[186:189], off
	s_nop 1
	s_mov_b64 s[98:99], 0x2c000
	v_lshl_add_u64 v[160:161], v[160:161], 0, s[98:99]
	v_mul_f32_e32 v166, 0xbfb8aa3b, v238
	v_mul_f32_e32 v168, v238, v238
	v_pk_mul_f32 v[170:171], v[24:25], v[166:167] op_sel_hi:[1,0]
	v_pk_mul_f32 v[172:173], v[26:27], v[166:167] op_sel_hi:[1,0]
	v_pk_mul_f32 v[174:175], v[16:17], v[166:167] op_sel_hi:[1,0]
	v_pk_mul_f32 v[176:177], v[18:19], v[166:167] op_sel_hi:[1,0]
	v_pk_mul_f32 v[178:179], v[24:25], v[28:29]
	v_pk_mul_f32 v[180:181], v[26:27], v[30:31]
	v_pk_mul_f32 v[182:183], v[16:17], v[20:21]
	v_pk_mul_f32 v[184:185], v[18:19], v[22:23]
	v_exp_f32_e32 v170, v170
	v_exp_f32_e32 v171, v171
	v_exp_f32_e32 v172, v172
	v_exp_f32_e32 v173, v173
	v_exp_f32_e32 v174, v174
	v_exp_f32_e32 v175, v175
	v_exp_f32_e32 v176, v176
	v_exp_f32_e32 v177, v177
	s_nop 0
	v_pk_add_f32 v[170:171], v[170:171], v[164:165]
	v_pk_add_f32 v[172:173], v[172:173], v[164:165]
	v_pk_add_f32 v[174:175], v[174:175], v[164:165]
	v_pk_add_f32 v[176:177], v[176:177], v[164:165]
	v_rcp_f32_e32 v170, v170
	v_rcp_f32_e32 v171, v171
	v_rcp_f32_e32 v172, v172
	v_rcp_f32_e32 v173, v173
	v_rcp_f32_e32 v174, v174
	v_rcp_f32_e32 v175, v175
	v_rcp_f32_e32 v176, v176
	v_rcp_f32_e32 v177, v177
	s_nop 0
	v_pk_mul_f32 v[170:171], v[170:171], v[168:169] op_sel_hi:[1,0]
	v_pk_mul_f32 v[172:173], v[172:173], v[168:169] op_sel_hi:[1,0]
	v_pk_mul_f32 v[174:175], v[174:175], v[168:169] op_sel_hi:[1,0]
	v_pk_mul_f32 v[176:177], v[176:177], v[168:169] op_sel_hi:[1,0]
	v_pk_mul_f32 v[178:179], v[178:179], v[170:171]
	v_pk_mul_f32 v[180:181], v[180:181], v[172:173]
	v_pk_mul_f32 v[182:183], v[182:183], v[174:175]
	v_pk_mul_f32 v[184:185], v[184:185], v[176:177]
	v_cvt_pk_bf16_f32 v186, v178, v179
	v_cvt_pk_bf16_f32 v187, v180, v181
	v_cvt_pk_bf16_f32 v188, v182, v183
	v_cvt_pk_bf16_f32 v189, v184, v185
	global_store_dwordx4 v[160:161], v[186:189], off
	s_nop 1
	s_mov_b64 s[98:99], 0x2c000
	v_lshl_add_u64 v[160:161], v[160:161], 0, s[98:99]
	v_mul_f32_e32 v166, 0xbfb8aa3b, v239
	v_mul_f32_e32 v168, v239, v239
	v_pk_mul_f32 v[170:171], v[8:9], v[166:167] op_sel_hi:[1,0]
	v_pk_mul_f32 v[172:173], v[10:11], v[166:167] op_sel_hi:[1,0]
	v_pk_mul_f32 v[174:175], v[4:5], v[166:167] op_sel_hi:[1,0]
	v_pk_mul_f32 v[176:177], v[6:7], v[166:167] op_sel_hi:[1,0]
	v_pk_mul_f32 v[178:179], v[8:9], v[12:13]
	v_pk_mul_f32 v[180:181], v[10:11], v[14:15]
	v_pk_mul_f32 v[182:183], v[4:5], v[0:1]
	v_pk_mul_f32 v[184:185], v[6:7], v[2:3]
	v_exp_f32_e32 v170, v170
	v_exp_f32_e32 v171, v171
	v_exp_f32_e32 v172, v172
	v_exp_f32_e32 v173, v173
	v_exp_f32_e32 v174, v174
	v_exp_f32_e32 v175, v175
	v_exp_f32_e32 v176, v176
	v_exp_f32_e32 v177, v177
	s_nop 0
	v_pk_add_f32 v[170:171], v[170:171], v[164:165]
	v_pk_add_f32 v[172:173], v[172:173], v[164:165]
	v_pk_add_f32 v[174:175], v[174:175], v[164:165]
	v_pk_add_f32 v[176:177], v[176:177], v[164:165]
	v_rcp_f32_e32 v170, v170
	v_rcp_f32_e32 v171, v171
	v_rcp_f32_e32 v172, v172
	v_rcp_f32_e32 v173, v173
	v_rcp_f32_e32 v174, v174
	v_rcp_f32_e32 v175, v175
	v_rcp_f32_e32 v176, v176
	v_rcp_f32_e32 v177, v177
	s_nop 0
	v_pk_mul_f32 v[170:171], v[170:171], v[168:169] op_sel_hi:[1,0]
	v_pk_mul_f32 v[172:173], v[172:173], v[168:169] op_sel_hi:[1,0]
	v_pk_mul_f32 v[174:175], v[174:175], v[168:169] op_sel_hi:[1,0]
	v_pk_mul_f32 v[176:177], v[176:177], v[168:169] op_sel_hi:[1,0]
	v_pk_mul_f32 v[178:179], v[178:179], v[170:171]
	v_pk_mul_f32 v[180:181], v[180:181], v[172:173]
	v_pk_mul_f32 v[182:183], v[182:183], v[174:175]
	v_pk_mul_f32 v[184:185], v[184:185], v[176:177]
	v_cvt_pk_bf16_f32 v186, v178, v179
	v_cvt_pk_bf16_f32 v187, v180, v181
	v_cvt_pk_bf16_f32 v188, v182, v183
	v_cvt_pk_bf16_f32 v189, v184, v185
	s_and_b64 vcc, exec, s[2:3]
	s_mov_b64 s[2:3], -1
	global_store_dwordx4 v[160:161], v[186:189], off
	s_cbranch_vccnz .LBB0_1486
	s_andn2_b64 vcc, exec, s[16:17]
	s_cbranch_vccnz .LBB0_1485
	s_barrier
	s_branch .LBB0_1485
